# P3 rebalanced again: retention part A tasks 0/4 and fold chunks 2/6 between GEMM and non-GEMM workgroups
# baseline (speedup 1.0000x reference)
; __device__ __forceinline__ int obid() { int b = (int)blockIdx.x; asm volatile("" : "+s"(b)); return b; }
; __device__ __forceinline__ void ph_mixA(const Params& p, int l, unsigned char* lds) {
;     const int G = gridDim.x, bid = obid();
;     for (int t = bid; t < 512 * REP_R1; t += G) ret1_task(p, l, t & 511, lds);
.LBB0_368:
	v_readlane_b32 s12, v255, 38
	s_lshl_b32 s3, s12, 3
	s_mov_b32 s92, s70
	s_cmpk_lt_i32 s92, 0x200
	s_cselect_b64 s[36:37], -1, 0
	s_cmpk_gt_i32 s92, 0x1ff
	s_mov_b32 s10, s92
	s_movk_i32 s6, 0x90
	s_mov_b32 s26, 0xbfb8aa3b
	s_mov_b32 s27, 0x42ce8ed0
	s_mov_b32 s43, 0xc2b17218
	s_mov_b32 s48, 0x7f800000
	s_mov_b32 s49, 0x3f2aaaab
	s_mov_b32 s50, 0x3f317218
	s_mov_b32 s51, 0x33800000
	s_mov_b32 s52, 0x6c00000
	s_mov_b64 s[54:55], 0xad20000
	s_mov_b64 s[56:57], 0x1c00
	s_mov_b64 s[58:59], 0x2000
	s_mov_b64 s[60:61], 0x6c00000
	v_readlane_b32 s13, v255, 39
	s_movk_i32 s98, 0x80
	s_sub_i32 s10, s92, s98
	s_cmp_lt_i32 s10, 0
	s_cselect_b32 s10, 0x200, s10
	s_cmpk_gt_i32 s10, 0x1ff
	s_cbranch_scc1 .LBB0_370

; __device__ __forceinline__ int obid() { int b = (int)blockIdx.x; asm volatile("" : "+s"(b)); return b; }
; __device__ __forceinline__ int otid() { int t; asm volatile("v_mov_b32 %0, %1" : "=v"(t) : "v"(threadIdx.x)); return t; }
; __device__ __forceinline__ unsigned pk2(float lo, float hi) { return f2bf(lo) | (f2bf(hi) << 16); }
; __device__ __forceinline__ float bf2f(bf16 b) { return __uint_as_float((unsigned)b << 16); }
; __device__ __forceinline__ float bflo(unsigned u) { return __uint_as_float(u << 16); }
; __device__ __forceinline__ float bfhi(unsigned u) { return __uint_as_float(u & 0xffff0000u); }
; __device__ __forceinline__ void ph_fold(const Params& p_) {
;     ...
;     for (int e = obid() * NTHR + otid(); e < NB * DG * 2 * 256; e += gridDim.x * NTHR) {
;         const int row = e >> 8, s0 = (e & 255) * 8, pq = row & 1;
;         const bf16* src = PQ + (size_t)row * 4096;
;         const u32x4 own = *(const u32x4*)(src + s0), low = *(const u32x4*)(src + 4096 - s0 - 8);
;         const float top = (s0 == 0) ? 0.f : bf2f(src[4096 - s0]);
;         const float sg = pq ? -1.f : 1.f;
;         float o[8];
;         o[0] = bflo(own.x) + sg * top;            o[1] = bfhi(own.x) + sg * bfhi(low.w);
;         o[2] = bflo(own.y) + sg * bflo(low.w);    o[3] = bfhi(own.y) + sg * bfhi(low.z);
;         o[4] = bflo(own.z) + sg * bflo(low.z);    o[5] = bfhi(own.z) + sg * bfhi(low.y);
;         o[6] = bflo(own.w) + sg * bflo(low.y);    o[7] = bfhi(own.w) + sg * bfhi(low.x);
;         if (s0 == 0 && pq) o[0] = 0.f;
;         u32x4 w; w.x = pk2(o[0], o[1]); w.y = pk2(o[2], o[3]); w.z = pk2(o[4], o[5]); w.w = pk2(o[6], o[7]);
;         *(u32x4*)(PQF + (size_t)row * 2048 + s0) = w;
;     }
.LBB0_451:
	s_mov_b64 s[36:37], s[0:1]
	s_mov_b32 s3, s70
	s_mov_b32 s54, 0x7ffff
	s_movk_i32 s55, 0x80
	s_cmp_lt_u32 s3, s55
	s_cselect_b32 s54, 0x2ffff, s54
	s_mov_b32 s55, 0x10000
	v_mov_b32 v0, v147
	s_mov_b32 s6, 0x80000
	v_lshl_add_u32 v14, s3, 9, v0
	v_cmp_gt_i32_e32 vcc, s6, v14
	s_and_saveexec_b64 s[12:13], vcc
	s_xor_b64 s[38:39], exec, s[12:13]
	s_movk_i32 s68, 0x800
	v_readlane_b32 s24, v255, 36
	s_cbranch_execz .LBB0_457
	s_load_dwordx2 s[12:13], s[36:37], 0x90
	v_lshlrev_b32_e32 v0, 3, v0
	v_lshl_add_u32 v15, s3, 12, v0
	s_mov_b64 s[44:45], 0
	s_waitcnt lgkmcnt(0)
	s_add_u32 s40, s12, 0x11520000
	s_addc_u32 s41, s13, 0
	s_add_u32 s42, s12, 0x6400000
	s_addc_u32 s43, s13, 0
	s_branch .LBB0_454
.LBB0_453:
	s_or_b64 exec, exec, s[46:47]
	v_and_b32_e32 v12, 0x100, v14
	v_cmp_ne_u32_e64 s[36:37], 0, v12
	s_waitcnt vmcnt(0)
	v_lshlrev_b32_e32 v13, 16, v6
	s_and_b64 s[12:13], s[36:37], vcc
	v_cndmask_b32_e64 v12, 1.0, -1.0, s[36:37]
	v_fmac_f32_e32 v13, v12, v17
	v_and_b32_e32 v6, 0xffff0000, v6
	v_and_b32_e32 v16, 0xffff0000, v5
	v_cndmask_b32_e64 v13, v13, 0, s[12:13]
	v_fmac_f32_e32 v6, v12, v16
	v_bfe_u32 v16, v13, 16, 1
	v_add3_u32 v13, v13, v16, s14
	v_lshrrev_b32_e32 v13, 16, v13
	v_bfe_u32 v16, v6, 16, 1
	v_lshlrev_b32_e32 v19, 16, v5
	v_lshlrev_b32_e32 v18, 16, v4
	v_add3_u32 v6, v6, v16, s14
	v_lshlrev_b32_e32 v17, 16, v8
	v_lshlrev_b32_e32 v16, 16, v7
	v_pk_mul_f32 v[18:19], v[12:13], v[18:19] op_sel_hi:[0,1]
	v_and_b32_e32 v5, 0xffff0000, v4
	v_and_b32_e32 v4, 0xffff0000, v3
	v_pk_add_f32 v[16:17], v[18:19], v[16:17] op_sel:[1,0] op_sel_hi:[0,1]
	v_and_b32_e32 v19, 0xffff0000, v8
	v_and_b32_e32 v18, 0xffff0000, v7
	v_pk_mul_f32 v[4:5], v[12:13], v[4:5] op_sel_hi:[0,1]
	v_pk_add_f32 v[4:5], v[4:5], v[18:19] op_sel:[1,0] op_sel_hi:[0,1]
	v_and_b32_sdwa v8, v16, v179 dst_sel:DWORD dst_unused:UNUSED_PAD src0_sel:WORD_1 src1_sel:DWORD
	v_and_or_b32 v6, v6, s15, v13
	v_add3_u32 v13, v16, v8, s14
	v_and_b32_sdwa v8, v5, v179 dst_sel:DWORD dst_unused:UNUSED_PAD src0_sel:WORD_1 src1_sel:DWORD
	v_and_b32_sdwa v16, v4, v179 dst_sel:DWORD dst_unused:UNUSED_PAD src0_sel:WORD_1 src1_sel:DWORD
	v_and_b32_sdwa v7, v17, v179 dst_sel:DWORD dst_unused:UNUSED_PAD src0_sel:WORD_1 src1_sel:DWORD
	v_add3_u32 v5, v5, v8, s14
	v_add3_u32 v4, v4, v16, s14
	v_add3_u32 v7, v17, v7, s14
	v_and_b32_e32 v5, 0xffff0000, v5
	v_and_b32_e32 v4, 0xffff0000, v4
	v_or_b32_sdwa v8, v5, v7 dst_sel:DWORD dst_unused:UNUSED_PAD src0_sel:DWORD src1_sel:WORD_1
	v_or_b32_sdwa v7, v4, v13 dst_sel:DWORD dst_unused:UNUSED_PAD src0_sel:DWORD src1_sel:WORD_1
	v_and_b32_e32 v4, 0xffff0000, v9
	v_lshlrev_b32_e32 v5, 16, v9
	v_and_b32_e32 v2, 0xffff0000, v2
	v_lshlrev_b32_e32 v3, 16, v3
	v_pk_fma_f32 v[2:3], v[12:13], v[2:3], v[4:5] op_sel_hi:[0,1,1]
	v_and_b32_sdwa v4, v3, v179 dst_sel:DWORD dst_unused:UNUSED_PAD src0_sel:WORD_1 src1_sel:DWORD
	v_and_b32_sdwa v5, v2, v179 dst_sel:DWORD dst_unused:UNUSED_PAD src0_sel:WORD_1 src1_sel:DWORD
	v_add3_u32 v3, v3, v4, s14
	v_add3_u32 v2, v2, v5, s14
	v_lshrrev_b32_e32 v3, 16, v3
	v_and_or_b32 v9, v2, s15, v3
	v_lshlrev_b64 v[2:3], 12, v[10:11]
	v_cmp_gt_i32_e32 vcc, 0x30000, v14
	s_nop 1
	v_cndmask_b32_e64 v20, 0, 1, vcc
	v_lshlrev_b32_e32 v20, 16, v20
	v_add3_u32 v14, v14, v20, s55
	s_mov_b32 s3, s54
	v_lshl_add_u64 v[2:3], s[42:43], 0, v[2:3]
	v_cmp_lt_i32_e32 vcc, s3, v14
	v_lshl_add_u64 v[2:3], v[2:3], 0, v[0:1]
	s_or_b64 s[44:45], vcc, s[44:45]
	v_add_u32_e32 v15, s24, v15
	global_store_dwordx4 v[2:3], v[6:9], off
	s_andn2_b64 exec, exec, s[44:45]
	s_cbranch_execz .LBB0_456
